# input-projection rope epilogue de-serialised: cos/sin table kept in 16 KiB static LDS, ds_read + lgkmcnt instead of global loads behind vmcnt(0); on E1+saddr base
# speedup vs baseline: 1.0046x; 1.0046x over previous
.LBB0_244:
	v_lshrrev_b32_e32 v11, 1, v10
	v_and_b32_e32 v11, 24, v11
	s_add_u32 s74, s34, 0x1c800000
	v_and_b32_e32 v159, 15, v10
	v_lshlrev_b32_e32 v12, 1, v11
	v_lshlrev_b32_e32 v10, 2, v10
	s_addc_u32 s75, s35, 0
	s_and_b32 s11, s2, 3
	s_lshl_b32 s15, s3, 6
	v_lshl_or_b32 v12, v159, 6, v12
	s_lshl_b32 s3, s3, 13
	v_and_b32_e32 v10, 32, v10
	s_add_i32 m0, s93, 0x18000
	v_lshl_add_u64 v[6:7], v[6:7], 0, s[42:43]
	v_bitop3_b32 v13, v12, s3, v10 bitop3:0xde
	s_lshl_b32 s3, s11, 12
	s_waitcnt vmcnt(2)
	s_barrier
	global_load_lds_dwordx4 v[6:7], off
	v_lshl_add_u64 v[4:5], v[4:5], 0, s[42:43]
	s_add_i32 m0, s93, 0x1a000
	s_add_i32 s46, s93, 0x8000
	s_add_i32 s48, s93, 0xa000
	global_load_lds_dwordx4 v[4:5], off
	v_lshl_add_u64 v[2:3], v[2:3], 0, s[42:43]
	s_mov_b32 m0, s46
	s_add_u32 s6, s26, 0x80080
	global_load_lds_dwordx4 v[2:3], off
	v_lshl_add_u64 v[2:3], v[8:9], 0, s[42:43]
	s_mov_b32 m0, s48
	s_addc_u32 s7, s27, 0
	global_load_lds_dwordx4 v[2:3], off
	s_add_i32 m0, s93, 0x1c000
	v_lshl_add_u64 v[2:3], s[6:7], 0, v[132:133]
	global_load_lds_dwordx4 v[2:3], off
	v_lshl_add_u64 v[2:3], s[6:7], 0, v[136:137]
	s_add_i32 m0, s93, 0x1e000
	s_cmpk_lt_u32 s28, 0x100
	global_load_lds_dwordx4 v[2:3], off
	v_bitop3_b32 v160, v12, s3, v10 bitop3:0xde
	s_cselect_b64 s[78:79], -1, 0
	s_bfe_u32 s3, s28, 0x10006
	s_lshl_b32 s2, s2, 6
	s_and_b32 s2, s2, 0x80
	s_lshl_b32 s6, s3, 5
	s_waitcnt vmcnt(6)
	s_or_b32 s6, s2, s6
	v_lshlrev_b32_e32 v202, 2, v11
	s_cmp_eq_u32 s3, 0
	v_lshl_add_u64 v[2:3], s[34:35], 0, v[202:203]
	s_mov_b64 s[2:3], 0x2c500000
	s_mov_b32 s52, 0
	s_cselect_b64 s[8:9], -1, 0
	v_or_b32_e32 v161, 16, v159
	v_or_b32_e32 v162, 32, v159
	v_or_b32_e32 v163, 48, v159
	v_lshl_add_u64 v[138:139], v[2:3], 0, s[2:3]
	v_add_u32_e32 v246, 0x24000, v202
	v_lshlrev_b32_e32 v247, 5, v0
	v_add_u32_e32 v248, 0x2c500000, v247
	v_mov_b32_e32 v249, 0
	v_lshl_add_u64 v[248:249], s[34:35], 0, v[248:249]
	v_add_u32_e32 v247, 0x24000, v247
	global_load_dwordx4 v[250:253], v[248:249], off
	s_waitcnt vmcnt(0)
	ds_write_b128 v247, v[250:253]
	s_waitcnt lgkmcnt(0)
	global_load_dwordx4 v[250:253], v[248:249], off offset:16
	s_waitcnt vmcnt(0)
	ds_write_b128 v247, v[250:253] offset:16
	v_or_b32_e32 v164, s6, v11
	v_lshl_or_b32 v165, s11, 5, v11
	s_lshr_b32 s2, s1, 3
	v_add_u32_e32 v166, 0, v13
	s_barrier
	v_writelane_b32 v254, s2, 38
	s_branch .LBB0_247

.LBB0_268:
	s_lshl_b32 s11, s10, 8
	s_add_i32 s11, s11, s15
	s_lshl_b32 s22, s20, 8
	v_or_b32_e32 v167, s11, v159
	s_cmp_lt_i32 s20, 5
	s_mov_b64 s[2:3], -1
	s_movk_i32 s54, 0x1000
	s_movk_i32 s56, 0x1800
	s_movk_i32 s58, 0x2ff
	s_mov_b32 s28, 0x3e6d3388
	s_mov_b32 s38, 0x3f07dc22
	s_mov_b32 s68, 0xbf3a00e3
	s_mov_b32 s72, 0x3f35f0e3
	s_mov_b32 s76, 0xbe11a98e
	s_mov_b32 s82, 0x3e027906
	s_mov_b32 s88, 0xbf38aa3b
	s_cbranch_scc0 .LBB0_287
	s_cmp_lt_i32 s10, 32
	s_cselect_b64 s[2:3], -1, 0
	s_bfe_u32 s26, s11, 0x50006
	s_cmp_gt_i32 s10, 31
	v_mov_b32_e32 v143, v117
	v_mov_b32_e32 v142, v116
	v_mov_b32_e32 v145, v115
	v_mov_b32_e32 v144, v114
	v_mov_b32_e32 v149, v121
	v_mov_b32_e32 v148, v120
	v_mov_b32_e32 v153, v119
	v_mov_b32_e32 v152, v118
	v_mov_b32_e32 v147, v125
	v_mov_b32_e32 v146, v124
	v_mov_b32_e32 v151, v123
	v_mov_b32_e32 v150, v122
	v_mov_b32_e32 v155, v129
	v_mov_b32_e32 v154, v128
	v_mov_b32_e32 v157, v127
	v_mov_b32_e32 v156, v126
	s_cbranch_scc1 .LBB0_271
	v_mov_b32_e32 v140, s26
	v_cndmask_b32_e64 v140, v159, v140, s[8:9]
	v_lshl_add_u32 v202, v140, 7, v246
	ds_read_b128 v[140:143], v202 offset:8208
	ds_read_b128 v[168:171], v202 offset:16
	ds_read_b128 v[152:155], v202 offset:8192
	ds_read_b128 v[172:175], v202
	s_waitcnt lgkmcnt(0)
	v_pk_mul_f32 v[144:145], v[116:117], v[142:143]
	v_pk_mul_f32 v[148:149], v[114:115], v[140:141]
	v_pk_mul_f32 v[142:143], v[124:125], v[142:143]
	v_pk_mul_f32 v[140:141], v[122:123], v[140:141]
	v_pk_fma_f32 v[146:147], v[124:125], v[170:171], v[144:145] neg_lo:[0,0,1] neg_hi:[0,0,1]
	v_pk_fma_f32 v[150:151], v[122:123], v[168:169], v[148:149] neg_lo:[0,0,1] neg_hi:[0,0,1]
	v_pk_fma_f32 v[142:143], v[116:117], v[170:171], v[142:143]
	v_pk_mul_f32 v[144:145], v[120:121], v[154:155]
	v_pk_mul_f32 v[148:149], v[118:119], v[152:153]
	v_pk_mul_f32 v[170:171], v[128:129], v[154:155]
	v_pk_mul_f32 v[152:153], v[126:127], v[152:153]
	v_pk_fma_f32 v[154:155], v[128:129], v[174:175], v[144:145] neg_lo:[0,0,1] neg_hi:[0,0,1]
	v_pk_fma_f32 v[156:157], v[126:127], v[172:173], v[148:149] neg_lo:[0,0,1] neg_hi:[0,0,1]
	v_pk_fma_f32 v[148:149], v[120:121], v[174:175], v[170:171]
	v_pk_fma_f32 v[152:153], v[118:119], v[172:173], v[152:153]
	v_pk_fma_f32 v[144:145], v[114:115], v[168:169], v[140:141]
.LBB0_271:
	v_or_b32_e32 v140, s22, v164
	v_mov_b64_e32 v[168:169], s[74:75]
	v_ashrrev_i32_e32 v141, 31, v140
	v_mad_i64_i32 v[168:169], s[10:11], v167, s56, v[168:169]
	v_lshl_add_u64 v[172:173], v[140:141], 1, v[168:169]
	v_cvt_pk_bf16_f32 v168, v156, v157
	v_cvt_pk_bf16_f32 v169, v154, v155
	v_cvt_pk_bf16_f32 v170, v150, v151
	v_cvt_pk_bf16_f32 v171, v146, v147
	global_store_dwordx4 v[172:173], v[168:171], off
	v_cvt_pk_bf16_f32 v146, v152, v153
	v_cvt_pk_bf16_f32 v147, v148, v149
	v_cvt_pk_bf16_f32 v148, v144, v145
	v_cvt_pk_bf16_f32 v149, v142, v143
	v_cndmask_b32_e64 v142, 0, 1, s[2:3]
	global_store_dwordx4 v[172:173], v[146:149], off offset:128
	v_cmp_ne_u32_e64 s[10:11], 1, v142
	s_andn2_b64 vcc, exec, s[2:3]
	v_mov_b32_e32 v143, v101
	v_mov_b32_e32 v142, v100
	v_mov_b32_e32 v145, v99
	v_mov_b32_e32 v144, v98
	v_mov_b32_e32 v149, v105
	v_mov_b32_e32 v148, v104
	v_mov_b32_e32 v153, v103
	v_mov_b32_e32 v152, v102
	v_mov_b32_e32 v147, v109
	v_mov_b32_e32 v146, v108
	v_mov_b32_e32 v151, v107
	v_mov_b32_e32 v150, v106
	v_mov_b32_e32 v155, v113
	v_mov_b32_e32 v154, v112
	v_mov_b32_e32 v157, v111
	v_mov_b32_e32 v156, v110
	s_cbranch_vccnz .LBB0_273
	v_mov_b32_e32 v142, s26
	v_cndmask_b32_e64 v142, v161, v142, s[8:9]
	v_lshl_add_u32 v202, v142, 7, v246
	ds_read_b128 v[142:145], v202 offset:8208
	ds_read_b128 v[168:171], v202 offset:16
	ds_read_b128 v[152:155], v202 offset:8192
	ds_read_b128 v[172:175], v202
	s_waitcnt lgkmcnt(0)
	v_pk_mul_f32 v[146:147], v[100:101], v[144:145]
	v_pk_mul_f32 v[148:149], v[98:99], v[142:143]
	v_pk_mul_f32 v[144:145], v[108:109], v[144:145]
	v_pk_mul_f32 v[176:177], v[106:107], v[142:143]
	v_pk_fma_f32 v[146:147], v[108:109], v[170:171], v[146:147] neg_lo:[0,0,1] neg_hi:[0,0,1]
	v_pk_fma_f32 v[150:151], v[106:107], v[168:169], v[148:149] neg_lo:[0,0,1] neg_hi:[0,0,1]
	v_pk_fma_f32 v[142:143], v[100:101], v[170:171], v[144:145]
	v_pk_mul_f32 v[144:145], v[104:105], v[154:155]
	v_pk_mul_f32 v[148:149], v[102:103], v[152:153]
	v_pk_mul_f32 v[170:171], v[112:113], v[154:155]
	v_pk_mul_f32 v[152:153], v[110:111], v[152:153]
	v_pk_fma_f32 v[154:155], v[112:113], v[174:175], v[144:145] neg_lo:[0,0,1] neg_hi:[0,0,1]
	v_pk_fma_f32 v[156:157], v[110:111], v[172:173], v[148:149] neg_lo:[0,0,1] neg_hi:[0,0,1]
	v_pk_fma_f32 v[148:149], v[104:105], v[174:175], v[170:171]
	v_pk_fma_f32 v[152:153], v[102:103], v[172:173], v[152:153]
	v_pk_fma_f32 v[144:145], v[98:99], v[168:169], v[176:177]
.LBB0_273:
	v_or_b32_e32 v170, 16, v167
	v_mov_b64_e32 v[168:169], s[74:75]
	v_mad_i64_i32 v[168:169], s[2:3], v170, s56, v[168:169]
	v_lshl_add_u64 v[172:173], v[140:141], 1, v[168:169]
	v_cvt_pk_bf16_f32 v168, v156, v157
	v_cvt_pk_bf16_f32 v169, v154, v155
	v_cvt_pk_bf16_f32 v170, v150, v151
	v_cvt_pk_bf16_f32 v171, v146, v147
	global_store_dwordx4 v[172:173], v[168:171], off
	v_cvt_pk_bf16_f32 v146, v152, v153
	v_cvt_pk_bf16_f32 v147, v148, v149
	v_cvt_pk_bf16_f32 v148, v144, v145
	v_cvt_pk_bf16_f32 v149, v142, v143
	global_store_dwordx4 v[172:173], v[146:149], off offset:128
	s_and_b64 vcc, exec, s[10:11]
	v_mov_b32_e32 v143, v85
	v_mov_b32_e32 v142, v84
	v_mov_b32_e32 v145, v83
	v_mov_b32_e32 v144, v82
	v_mov_b32_e32 v149, v89
	v_mov_b32_e32 v148, v88
	v_mov_b32_e32 v153, v87
	v_mov_b32_e32 v152, v86
	v_mov_b32_e32 v147, v93
	v_mov_b32_e32 v146, v92
	v_mov_b32_e32 v151, v91
	v_mov_b32_e32 v150, v90
	v_mov_b32_e32 v155, v97
	v_mov_b32_e32 v154, v96
	v_mov_b32_e32 v157, v95
	v_mov_b32_e32 v156, v94
	s_cbranch_vccnz .LBB0_275
	v_mov_b32_e32 v142, s26
	v_cndmask_b32_e64 v142, v162, v142, s[8:9]
	v_lshl_add_u32 v202, v142, 7, v246
	ds_read_b128 v[142:145], v202 offset:8208
	ds_read_b128 v[168:171], v202 offset:16
	ds_read_b128 v[152:155], v202 offset:8192
	ds_read_b128 v[172:175], v202
	s_waitcnt lgkmcnt(0)
	v_pk_mul_f32 v[146:147], v[84:85], v[144:145]
	v_pk_mul_f32 v[148:149], v[82:83], v[142:143]
	v_pk_mul_f32 v[144:145], v[92:93], v[144:145]
	v_pk_mul_f32 v[176:177], v[90:91], v[142:143]
	v_pk_fma_f32 v[146:147], v[92:93], v[170:171], v[146:147] neg_lo:[0,0,1] neg_hi:[0,0,1]
	v_pk_fma_f32 v[150:151], v[90:91], v[168:169], v[148:149] neg_lo:[0,0,1] neg_hi:[0,0,1]
	v_pk_fma_f32 v[142:143], v[84:85], v[170:171], v[144:145]
	v_pk_mul_f32 v[144:145], v[88:89], v[154:155]
	v_pk_mul_f32 v[148:149], v[86:87], v[152:153]
	v_pk_mul_f32 v[170:171], v[96:97], v[154:155]
	v_pk_mul_f32 v[152:153], v[94:95], v[152:153]
	v_pk_fma_f32 v[154:155], v[96:97], v[174:175], v[144:145] neg_lo:[0,0,1] neg_hi:[0,0,1]
	v_pk_fma_f32 v[156:157], v[94:95], v[172:173], v[148:149] neg_lo:[0,0,1] neg_hi:[0,0,1]
	v_pk_fma_f32 v[148:149], v[88:89], v[174:175], v[170:171]
	v_pk_fma_f32 v[152:153], v[86:87], v[172:173], v[152:153]
	v_pk_fma_f32 v[144:145], v[82:83], v[168:169], v[176:177]
.LBB0_275:
	v_or_b32_e32 v170, 32, v167
	v_mov_b64_e32 v[168:169], s[74:75]
	v_mad_i64_i32 v[168:169], s[2:3], v170, s56, v[168:169]
	v_lshl_add_u64 v[172:173], v[140:141], 1, v[168:169]
	v_cvt_pk_bf16_f32 v168, v156, v157
	v_cvt_pk_bf16_f32 v169, v154, v155
	v_cvt_pk_bf16_f32 v170, v150, v151
	v_cvt_pk_bf16_f32 v171, v146, v147
	global_store_dwordx4 v[172:173], v[168:171], off
	v_cvt_pk_bf16_f32 v146, v152, v153
	v_cvt_pk_bf16_f32 v147, v148, v149
	v_cvt_pk_bf16_f32 v148, v144, v145
	v_cvt_pk_bf16_f32 v149, v142, v143
	global_store_dwordx4 v[172:173], v[146:149], off offset:128
	s_and_b64 vcc, exec, s[10:11]
	v_mov_b32_e32 v143, v69
	v_mov_b32_e32 v142, v68
	v_mov_b32_e32 v145, v67
	v_mov_b32_e32 v144, v66
	v_mov_b32_e32 v149, v73
	v_mov_b32_e32 v148, v72
	v_mov_b32_e32 v153, v71
	v_mov_b32_e32 v152, v70
	v_mov_b32_e32 v147, v77
	v_mov_b32_e32 v146, v76
	v_mov_b32_e32 v151, v75
	v_mov_b32_e32 v150, v74
	v_mov_b32_e32 v155, v81
	v_mov_b32_e32 v154, v80
	v_mov_b32_e32 v157, v79
	v_mov_b32_e32 v156, v78
	s_cbranch_vccnz .LBB0_277
	v_mov_b32_e32 v142, s26
	v_cndmask_b32_e64 v142, v163, v142, s[8:9]
	v_lshl_add_u32 v202, v142, 7, v246
	ds_read_b128 v[142:145], v202 offset:8208
	ds_read_b128 v[168:171], v202 offset:16
	ds_read_b128 v[152:155], v202 offset:8192
	ds_read_b128 v[172:175], v202
	s_waitcnt lgkmcnt(0)
	v_pk_mul_f32 v[146:147], v[68:69], v[144:145]
	v_pk_mul_f32 v[148:149], v[66:67], v[142:143]
	v_pk_mul_f32 v[144:145], v[76:77], v[144:145]
	v_pk_mul_f32 v[176:177], v[74:75], v[142:143]
	v_pk_fma_f32 v[146:147], v[76:77], v[170:171], v[146:147] neg_lo:[0,0,1] neg_hi:[0,0,1]
	v_pk_fma_f32 v[150:151], v[74:75], v[168:169], v[148:149] neg_lo:[0,0,1] neg_hi:[0,0,1]
	v_pk_fma_f32 v[142:143], v[68:69], v[170:171], v[144:145]
	v_pk_mul_f32 v[144:145], v[72:73], v[154:155]
	v_pk_mul_f32 v[148:149], v[70:71], v[152:153]
	v_pk_mul_f32 v[170:171], v[80:81], v[154:155]
	v_pk_mul_f32 v[152:153], v[78:79], v[152:153]
	v_pk_fma_f32 v[154:155], v[80:81], v[174:175], v[144:145] neg_lo:[0,0,1] neg_hi:[0,0,1]
	v_pk_fma_f32 v[156:157], v[78:79], v[172:173], v[148:149] neg_lo:[0,0,1] neg_hi:[0,0,1]
	v_pk_fma_f32 v[148:149], v[72:73], v[174:175], v[170:171]
	v_pk_fma_f32 v[152:153], v[70:71], v[172:173], v[152:153]
	v_pk_fma_f32 v[144:145], v[66:67], v[168:169], v[176:177]
.LBB0_277:
	v_or_b32_e32 v170, 48, v167
	v_mov_b64_e32 v[168:169], s[74:75]
	v_mad_i64_i32 v[168:169], s[2:3], v170, s56, v[168:169]
	v_lshl_add_u64 v[172:173], v[140:141], 1, v[168:169]
	v_cvt_pk_bf16_f32 v168, v156, v157
	v_cvt_pk_bf16_f32 v169, v154, v155
	v_cvt_pk_bf16_f32 v170, v150, v151
	v_cvt_pk_bf16_f32 v171, v146, v147
	global_store_dwordx4 v[172:173], v[168:171], off
	v_cvt_pk_bf16_f32 v146, v152, v153
	v_cvt_pk_bf16_f32 v147, v148, v149
	v_cvt_pk_bf16_f32 v148, v144, v145
	v_cvt_pk_bf16_f32 v149, v142, v143
	global_store_dwordx4 v[172:173], v[146:149], off offset:128
	s_nop 0
	v_add_u32_e32 v169, 0x80, v167
	v_bfe_u32 v168, v169, 6, 5
	s_and_b64 vcc, exec, s[10:11]
	v_mov_b32_e32 v143, v53
	v_mov_b32_e32 v142, v52
	v_mov_b32_e32 v145, v51
	v_mov_b32_e32 v144, v50
	v_mov_b32_e32 v149, v57
	v_mov_b32_e32 v148, v56
	v_mov_b32_e32 v153, v55
	v_mov_b32_e32 v152, v54
	v_mov_b32_e32 v147, v61
	v_mov_b32_e32 v146, v60
	v_mov_b32_e32 v151, v59
	v_mov_b32_e32 v150, v58
	v_mov_b32_e32 v155, v65
	v_mov_b32_e32 v154, v64
	v_mov_b32_e32 v157, v63
	v_mov_b32_e32 v156, v62
	s_cbranch_vccnz .LBB0_279
	v_cndmask_b32_e64 v142, v159, v168, s[8:9]
	v_lshl_add_u32 v202, v142, 7, v246
	ds_read_b128 v[142:145], v202 offset:8208
	ds_read_b128 v[170:173], v202 offset:16
	ds_read_b128 v[152:155], v202 offset:8192
	ds_read_b128 v[174:177], v202
	s_waitcnt lgkmcnt(0)
	v_pk_mul_f32 v[146:147], v[52:53], v[144:145]
	v_pk_mul_f32 v[148:149], v[50:51], v[142:143]
	v_pk_mul_f32 v[144:145], v[60:61], v[144:145]
	v_pk_mul_f32 v[178:179], v[58:59], v[142:143]
	v_pk_fma_f32 v[146:147], v[60:61], v[172:173], v[146:147] neg_lo:[0,0,1] neg_hi:[0,0,1]
	v_pk_fma_f32 v[150:151], v[58:59], v[170:171], v[148:149] neg_lo:[0,0,1] neg_hi:[0,0,1]
	v_pk_fma_f32 v[142:143], v[52:53], v[172:173], v[144:145]
	v_pk_mul_f32 v[144:145], v[56:57], v[154:155]
	v_pk_mul_f32 v[148:149], v[54:55], v[152:153]
	v_pk_mul_f32 v[172:173], v[64:65], v[154:155]
	v_pk_mul_f32 v[152:153], v[62:63], v[152:153]
	v_pk_fma_f32 v[154:155], v[64:65], v[176:177], v[144:145] neg_lo:[0,0,1] neg_hi:[0,0,1]
	v_pk_fma_f32 v[156:157], v[62:63], v[174:175], v[148:149] neg_lo:[0,0,1] neg_hi:[0,0,1]
	v_pk_fma_f32 v[148:149], v[56:57], v[176:177], v[172:173]
	v_pk_fma_f32 v[152:153], v[54:55], v[174:175], v[152:153]
	v_pk_fma_f32 v[144:145], v[50:51], v[170:171], v[178:179]
.LBB0_279:
	v_mov_b64_e32 v[170:171], s[74:75]
	v_mad_i64_i32 v[170:171], s[2:3], v169, s56, v[170:171]
	v_lshl_add_u64 v[174:175], v[140:141], 1, v[170:171]
	v_cvt_pk_bf16_f32 v170, v156, v157
	v_cvt_pk_bf16_f32 v171, v154, v155
	v_cvt_pk_bf16_f32 v172, v150, v151
	v_cvt_pk_bf16_f32 v173, v146, v147
	global_store_dwordx4 v[174:175], v[170:173], off
	v_cvt_pk_bf16_f32 v146, v152, v153
	v_cvt_pk_bf16_f32 v147, v148, v149
	v_cvt_pk_bf16_f32 v148, v144, v145
	v_cvt_pk_bf16_f32 v149, v142, v143
	global_store_dwordx4 v[174:175], v[146:149], off offset:128
	s_and_b64 vcc, exec, s[10:11]
	v_mov_b32_e32 v143, v37
	v_mov_b32_e32 v142, v36
	v_mov_b32_e32 v145, v35
	v_mov_b32_e32 v144, v34
	v_mov_b32_e32 v149, v41
	v_mov_b32_e32 v148, v40
	v_mov_b32_e32 v153, v39
	v_mov_b32_e32 v152, v38
	v_mov_b32_e32 v147, v45
	v_mov_b32_e32 v146, v44
	v_mov_b32_e32 v151, v43
	v_mov_b32_e32 v150, v42
	v_mov_b32_e32 v155, v49
	v_mov_b32_e32 v154, v48
	v_mov_b32_e32 v157, v47
	v_mov_b32_e32 v156, v46
	s_cbranch_vccnz .LBB0_281
	v_cndmask_b32_e64 v142, v161, v168, s[8:9]
	v_lshl_add_u32 v202, v142, 7, v246
	ds_read_b128 v[142:145], v202 offset:8208
	ds_read_b128 v[170:173], v202 offset:16
	ds_read_b128 v[152:155], v202 offset:8192
	ds_read_b128 v[174:177], v202
	s_waitcnt lgkmcnt(0)
	v_pk_mul_f32 v[146:147], v[36:37], v[144:145]
	v_pk_mul_f32 v[148:149], v[34:35], v[142:143]
	v_pk_mul_f32 v[144:145], v[44:45], v[144:145]
	v_pk_mul_f32 v[178:179], v[42:43], v[142:143]
	v_pk_fma_f32 v[146:147], v[44:45], v[172:173], v[146:147] neg_lo:[0,0,1] neg_hi:[0,0,1]
	v_pk_fma_f32 v[150:151], v[42:43], v[170:171], v[148:149] neg_lo:[0,0,1] neg_hi:[0,0,1]
	v_pk_fma_f32 v[142:143], v[36:37], v[172:173], v[144:145]
	v_pk_mul_f32 v[144:145], v[40:41], v[154:155]
	v_pk_mul_f32 v[148:149], v[38:39], v[152:153]
	v_pk_mul_f32 v[172:173], v[48:49], v[154:155]
	v_pk_mul_f32 v[152:153], v[46:47], v[152:153]
	v_pk_fma_f32 v[154:155], v[48:49], v[176:177], v[144:145] neg_lo:[0,0,1] neg_hi:[0,0,1]
	v_pk_fma_f32 v[156:157], v[46:47], v[174:175], v[148:149] neg_lo:[0,0,1] neg_hi:[0,0,1]
	v_pk_fma_f32 v[148:149], v[40:41], v[176:177], v[172:173]
	v_pk_fma_f32 v[152:153], v[38:39], v[174:175], v[152:153]
	v_pk_fma_f32 v[144:145], v[34:35], v[170:171], v[178:179]
.LBB0_281:
	v_add_u32_e32 v169, 0x90, v167
	v_mov_b64_e32 v[170:171], s[74:75]
	v_mad_i64_i32 v[170:171], s[2:3], v169, s56, v[170:171]
	v_lshl_add_u64 v[174:175], v[140:141], 1, v[170:171]
	v_cvt_pk_bf16_f32 v170, v156, v157
	v_cvt_pk_bf16_f32 v171, v154, v155
	v_cvt_pk_bf16_f32 v172, v150, v151
	v_cvt_pk_bf16_f32 v173, v146, v147
	global_store_dwordx4 v[174:175], v[170:173], off
	v_cvt_pk_bf16_f32 v146, v152, v153
	v_cvt_pk_bf16_f32 v147, v148, v149
	v_cvt_pk_bf16_f32 v148, v144, v145
	v_cvt_pk_bf16_f32 v149, v142, v143
	global_store_dwordx4 v[174:175], v[146:149], off offset:128
	s_and_b64 vcc, exec, s[10:11]
	v_mov_b32_e32 v143, v21
	v_mov_b32_e32 v142, v20
	v_mov_b32_e32 v145, v19
	v_mov_b32_e32 v144, v18
	v_mov_b32_e32 v149, v25
	v_mov_b32_e32 v148, v24
	v_mov_b32_e32 v153, v23
	v_mov_b32_e32 v152, v22
	v_mov_b32_e32 v147, v29
	v_mov_b32_e32 v146, v28
	v_mov_b32_e32 v151, v27
	v_mov_b32_e32 v150, v26
	v_mov_b32_e32 v155, v33
	v_mov_b32_e32 v154, v32
	v_mov_b32_e32 v157, v31
	v_mov_b32_e32 v156, v30
	s_cbranch_vccnz .LBB0_283
	v_cndmask_b32_e64 v142, v162, v168, s[8:9]
	v_lshl_add_u32 v202, v142, 7, v246
	ds_read_b128 v[142:145], v202 offset:8208
	ds_read_b128 v[170:173], v202 offset:16
	ds_read_b128 v[152:155], v202 offset:8192
	ds_read_b128 v[174:177], v202
	s_waitcnt lgkmcnt(0)
	v_pk_mul_f32 v[146:147], v[20:21], v[144:145]
	v_pk_mul_f32 v[148:149], v[18:19], v[142:143]
	v_pk_mul_f32 v[144:145], v[28:29], v[144:145]
	v_pk_mul_f32 v[178:179], v[26:27], v[142:143]
	v_pk_fma_f32 v[146:147], v[28:29], v[172:173], v[146:147] neg_lo:[0,0,1] neg_hi:[0,0,1]
	v_pk_fma_f32 v[150:151], v[26:27], v[170:171], v[148:149] neg_lo:[0,0,1] neg_hi:[0,0,1]
	v_pk_fma_f32 v[142:143], v[20:21], v[172:173], v[144:145]
	v_pk_mul_f32 v[144:145], v[24:25], v[154:155]
	v_pk_mul_f32 v[148:149], v[22:23], v[152:153]
	v_pk_mul_f32 v[172:173], v[32:33], v[154:155]
	v_pk_mul_f32 v[152:153], v[30:31], v[152:153]
	v_pk_fma_f32 v[154:155], v[32:33], v[176:177], v[144:145] neg_lo:[0,0,1] neg_hi:[0,0,1]
	v_pk_fma_f32 v[156:157], v[30:31], v[174:175], v[148:149] neg_lo:[0,0,1] neg_hi:[0,0,1]
	v_pk_fma_f32 v[148:149], v[24:25], v[176:177], v[172:173]
	v_pk_fma_f32 v[152:153], v[22:23], v[174:175], v[152:153]
	v_pk_fma_f32 v[144:145], v[18:19], v[170:171], v[178:179]
.LBB0_283:
	v_add_u32_e32 v169, 0xa0, v167
	v_mov_b64_e32 v[170:171], s[74:75]
	v_mad_i64_i32 v[170:171], s[2:3], v169, s56, v[170:171]
	v_lshl_add_u64 v[174:175], v[140:141], 1, v[170:171]
	v_cvt_pk_bf16_f32 v170, v156, v157
	v_cvt_pk_bf16_f32 v171, v154, v155
	v_cvt_pk_bf16_f32 v172, v150, v151
	v_cvt_pk_bf16_f32 v173, v146, v147
	global_store_dwordx4 v[174:175], v[170:173], off
	v_cvt_pk_bf16_f32 v146, v152, v153
	v_cvt_pk_bf16_f32 v147, v148, v149
	v_cvt_pk_bf16_f32 v148, v144, v145
	v_cvt_pk_bf16_f32 v149, v142, v143
	global_store_dwordx4 v[174:175], v[146:149], off offset:128
	s_and_b64 vcc, exec, s[10:11]
	v_mov_b32_e32 v143, v5
	v_mov_b32_e32 v142, v4
	v_mov_b32_e32 v145, v3
	v_mov_b32_e32 v144, v2
	v_mov_b32_e32 v147, v9
	v_mov_b32_e32 v146, v8
	v_mov_b32_e32 v151, v7
	v_mov_b32_e32 v150, v6
	v_mov_b32_e32 v149, v13
	v_mov_b32_e32 v148, v12
	v_mov_b32_e32 v153, v11
	v_mov_b32_e32 v152, v10
	v_mov_b32_e32 v155, v17
	v_mov_b32_e32 v154, v16
	v_mov_b32_e32 v157, v15
	v_mov_b32_e32 v156, v14
	s_cbranch_vccnz .LBB0_285
	v_cndmask_b32_e64 v142, v163, v168, s[8:9]
	v_lshl_add_u32 v202, v142, 7, v246
	ds_read_b128 v[142:145], v202 offset:8208
	ds_read_b128 v[168:171], v202 offset:16
	ds_read_b128 v[154:157], v202 offset:8192
	ds_read_b128 v[172:175], v202
	s_waitcnt lgkmcnt(0)
	v_pk_mul_f32 v[146:147], v[4:5], v[144:145]
	v_pk_mul_f32 v[150:151], v[2:3], v[142:143]
	v_pk_mul_f32 v[144:145], v[12:13], v[144:145]
	v_pk_mul_f32 v[176:177], v[10:11], v[142:143]
	v_pk_fma_f32 v[148:149], v[12:13], v[170:171], v[146:147] neg_lo:[0,0,1] neg_hi:[0,0,1]
	v_pk_fma_f32 v[152:153], v[10:11], v[168:169], v[150:151] neg_lo:[0,0,1] neg_hi:[0,0,1]
	v_pk_fma_f32 v[142:143], v[4:5], v[170:171], v[144:145]
	v_pk_mul_f32 v[144:145], v[8:9], v[156:157]
	v_pk_mul_f32 v[146:147], v[6:7], v[154:155]
	v_pk_mul_f32 v[150:151], v[16:17], v[156:157]
	v_pk_mul_f32 v[170:171], v[14:15], v[154:155]
	v_pk_fma_f32 v[154:155], v[16:17], v[174:175], v[144:145] neg_lo:[0,0,1] neg_hi:[0,0,1]
	v_pk_fma_f32 v[156:157], v[14:15], v[172:173], v[146:147] neg_lo:[0,0,1] neg_hi:[0,0,1]
	v_pk_fma_f32 v[146:147], v[8:9], v[174:175], v[150:151]
	v_pk_fma_f32 v[150:151], v[6:7], v[172:173], v[170:171]
	v_pk_fma_f32 v[144:145], v[2:3], v[168:169], v[176:177]

	.amdhsa_kernel _Z10fwd_kernel6Params
		.amdhsa_group_segment_fixed_size 16384
		.amdhsa_private_segment_fixed_size 0
		.amdhsa_kernarg_size 424
		.amdhsa_user_sgpr_count 2
		.amdhsa_user_sgpr_dispatch_ptr 0
		.amdhsa_user_sgpr_queue_ptr 0
		.amdhsa_user_sgpr_kernarg_segment_ptr 1
		.amdhsa_user_sgpr_dispatch_id 0
		.amdhsa_user_sgpr_kernarg_preload_length 0
		.amdhsa_user_sgpr_kernarg_preload_offset 0
		.amdhsa_user_sgpr_private_segment_size 0
		.amdhsa_uses_dynamic_stack 0
		.amdhsa_enable_private_segment 0
		.amdhsa_system_sgpr_workgroup_id_x 1
		.amdhsa_system_sgpr_workgroup_id_y 0
		.amdhsa_system_sgpr_workgroup_id_z 0
		.amdhsa_system_sgpr_workgroup_info 0
		.amdhsa_system_vgpr_workitem_id 0
		.amdhsa_next_free_vgpr 255
		.amdhsa_next_free_sgpr 100
		.amdhsa_accum_offset 256
		.amdhsa_reserve_vcc 1
		.amdhsa_float_round_mode_32 0
		.amdhsa_float_round_mode_16_64 0
		.amdhsa_float_denorm_mode_32 3
		.amdhsa_float_denorm_mode_16_64 3
		.amdhsa_dx10_clamp 1
		.amdhsa_ieee_mode 1
		.amdhsa_fp16_overflow 0
		.amdhsa_tg_split 0
		.amdhsa_exception_fp_ieee_invalid_op 0
		.amdhsa_exception_fp_denorm_src 0
		.amdhsa_exception_fp_ieee_div_zero 0
		.amdhsa_exception_fp_ieee_overflow 0
		.amdhsa_exception_fp_ieee_underflow 0
		.amdhsa_exception_fp_ieee_inexact 0
		.amdhsa_exception_int_div_zero 0
	.end_amdhsa_kernel

amdhsa.kernels:
  - .agpr_count:     0
    .args:
      - .offset:         0
        .size:           168
        .value_kind:     by_value
      - .offset:         168
        .size:           4
        .value_kind:     hidden_block_count_x
      - .offset:         172
        .size:           4
        .value_kind:     hidden_block_count_y
      - .offset:         176
        .size:           4
        .value_kind:     hidden_block_count_z
      - .offset:         180
        .size:           2
        .value_kind:     hidden_group_size_x
      - .offset:         182
        .size:           2
        .value_kind:     hidden_group_size_y
      - .offset:         184
        .size:           2
        .value_kind:     hidden_group_size_z
      - .offset:         186
        .size:           2
        .value_kind:     hidden_remainder_x
      - .offset:         188
        .size:           2
        .value_kind:     hidden_remainder_y
      - .offset:         190
        .size:           2
        .value_kind:     hidden_remainder_z
      - .offset:         208
        .size:           8
        .value_kind:     hidden_global_offset_x
      - .offset:         216
        .size:           8
        .value_kind:     hidden_global_offset_y
      - .offset:         224
        .size:           8
        .value_kind:     hidden_global_offset_z
      - .offset:         232
        .size:           2
        .value_kind:     hidden_grid_dims
      - .offset:         288
        .size:           4
        .value_kind:     hidden_dynamic_lds_size
    .group_segment_fixed_size: 16384
    .kernarg_segment_align: 8
    .kernarg_segment_size: 424
    .language:       OpenCL C
    .language_version:
      - 2
      - 0
    .max_flat_workgroup_size: 512
    .name:           _Z10fwd_kernel6Params
    .private_segment_fixed_size: 0
    .sgpr_count:     106
    .sgpr_spill_count: 70
    .symbol:         _Z10fwd_kernel6Params.kd
    .uniform_work_group_size: 1
    .uses_dynamic_stack: false
    .vgpr_count:     255
    .vgpr_spill_count: 0
    .wavefront_size: 64
